# grid barrier: non-leader workgroups poll the top generation word directly instead of waiting for their XCD leader to re-publish it through the per-XCD generation word (5 sites)
# speedup vs baseline: 1.0077x; 1.0077x over previous
; DI unsigned xb_ld(unsigned* p)              { return __hip_atomic_load(p, __ATOMIC_RELAXED, __HIP_MEMORY_SCOPE_AGENT); }
; DI unsigned xb_add(unsigned* p, unsigned v) { return __hip_atomic_fetch_add(p, v, __ATOMIC_RELAXED, __HIP_MEMORY_SCOPE_AGENT); }
; #define XB_SPIN(cond, bar) do { unsigned _sp = 0; while (cond) { __builtin_amdgcn_s_sleep(1); \
;     if ((++_sp & 255u) == 0u) { if (xb_ld(&(bar)[XB_TMO])) break; if (_sp > XB_SPIN_CAP) { atomicAdd(&(bar)[XB_TMO], 1u); break; } } } } while (0)
; DI void xcd_barrier(const XcdBarrier& b) {
;     ...
;         const unsigned old = xb_add(&bar[XB_XSUB(b.x)], 1u);
;         const unsigned gen = old / nloc;
;         if (old + 1u == (gen + 1u) * nloc) {
;             __builtin_amdgcn_fence(__ATOMIC_RELEASE, "agent");
;             asm volatile("s_waitcnt vmcnt(0)" ::: "memory");
;             const unsigned og = xb_add(&bar[XB_TOP], 1u);
;             const unsigned tg = og / nx;
;             if (og + 1u == (tg + 1u) * nx) xb_add(&bar[XB_TOPGEN], 1u);
;             else XB_SPIN(xb_ld(&bar[XB_TOPGEN]) == tg, bar);
;             __builtin_amdgcn_fence(__ATOMIC_ACQUIRE, "agent");
;             xb_add(&bar[XB_XGEN(b.x)], 1u);
;             asm volatile("s_waitcnt vmcnt(0)" ::: "memory");
;         } else {
;             XB_SPIN(xb_ld(&bar[XB_XGEN(b.x)]) == gen, bar);
;             __builtin_amdgcn_fence(__ATOMIC_ACQUIRE, "agent");
;             asm volatile("s_waitcnt vmcnt(0)" ::: "memory");
;         }
.LBB0_124:
	s_or_b64 exec, exec, s[10:11]
	v_cvt_f32_u32_e32 v4, v2
	s_waitcnt vmcnt(0)
	v_readfirstlane_b32 s0, v3
	v_sub_u32_e32 v3, 0, v2
	v_rcp_iflag_f32_e32 v4, v4
	v_add_u32_e32 v5, s0, v1
	v_mul_f32_e32 v4, 0x4f7ffffe, v4
	v_cvt_u32_f32_e32 v4, v4
	v_mul_lo_u32 v1, v3, v4
	v_mul_hi_u32 v1, v4, v1
	v_add_u32_e32 v1, v4, v1
	v_mul_hi_u32 v1, v5, v1
	v_mul_lo_u32 v3, v1, v2
	v_sub_u32_e32 v3, v5, v3
	v_add_u32_e32 v4, 1, v1
	v_cmp_ge_u32_e32 vcc, v3, v2
	s_nop 1
	v_cndmask_b32_e32 v1, v1, v4, vcc
	v_sub_u32_e32 v4, v3, v2
	v_cndmask_b32_e32 v3, v3, v4, vcc
	v_add_u32_e32 v4, 1, v1
	v_cmp_ge_u32_e32 vcc, v3, v2
	v_add_u32_e32 v3, 1, v5
	s_nop 0
	v_cndmask_b32_e32 v1, v1, v4, vcc
	v_mul_lo_u32 v4, v2, v1
	v_add_u32_e32 v2, v4, v2
	v_cmp_ne_u32_e32 vcc, v3, v2
	s_and_saveexec_b64 s[0:1], vcc
	s_xor_b64 s[8:9], exec, s[0:1]
	s_cbranch_execz .LBB0_138
	s_waitcnt lgkmcnt(0)
	s_add_u32 s16, s70, 0xff20500
	s_addc_u32 s17, s71, 0
	v_mov_b32_e32 v0, 0
	global_load_dword v0, v0, s[16:17] sc1
	s_waitcnt vmcnt(0)
	v_cmp_eq_u32_e32 vcc, 0, v0
	s_and_saveexec_b64 s[10:11], vcc
	s_cbranch_execz .LBB0_137
	s_add_u32 s12, s70, 0xff1d200
	s_addc_u32 s13, s71, 0
	s_mov_b32 s0, 1
	s_mov_b64 s[18:19], 0
	v_mov_b32_e32 v0, 0
	s_branch .LBB0_128

; DI unsigned xb_ld(unsigned* p)              { return __hip_atomic_load(p, __ATOMIC_RELAXED, __HIP_MEMORY_SCOPE_AGENT); }
; #define XB_SPIN(cond, bar) do { unsigned _sp = 0; while (cond) { __builtin_amdgcn_s_sleep(1); \
;     if ((++_sp & 255u) == 0u) { if (xb_ld(&(bar)[XB_TMO])) break; if (_sp > XB_SPIN_CAP) { atomicAdd(&(bar)[XB_TMO], 1u); break; } } } } while (0)
; DI void xcd_barrier(const XcdBarrier& b) {
;     ...
;             XB_SPIN(xb_ld(&bar[XB_XGEN(b.x)]) == gen, bar);
.LBB0_130:
	global_load_dword v2, v0, s[16:17] sc1
	s_add_i32 s0, s0, 1
	s_mov_b64 s[24:25], -1
	s_waitcnt vmcnt(0)
	v_cmp_ne_u32_e32 vcc, 0, v2
	s_orn2_b64 s[22:23], vcc, exec
	s_branch .LBB0_127

; DI unsigned xb_ld(unsigned* p)              { return __hip_atomic_load(p, __ATOMIC_RELAXED, __HIP_MEMORY_SCOPE_AGENT); }
; DI unsigned xb_add(unsigned* p, unsigned v) { return __hip_atomic_fetch_add(p, v, __ATOMIC_RELAXED, __HIP_MEMORY_SCOPE_AGENT); }
; #define XB_SPIN(cond, bar) do { unsigned _sp = 0; while (cond) { __builtin_amdgcn_s_sleep(1); \
;     if ((++_sp & 255u) == 0u) { if (xb_ld(&(bar)[XB_TMO])) break; if (_sp > XB_SPIN_CAP) { atomicAdd(&(bar)[XB_TMO], 1u); break; } } } } while (0)
; DI void xcd_barrier(const XcdBarrier& b) {
;     ...
;         const unsigned old = xb_add(&bar[XB_XSUB(b.x)], 1u);
;         const unsigned gen = old / nloc;
;         if (old + 1u == (gen + 1u) * nloc) {
;             __builtin_amdgcn_fence(__ATOMIC_RELEASE, "agent");
;             asm volatile("s_waitcnt vmcnt(0)" ::: "memory");
;             const unsigned og = xb_add(&bar[XB_TOP], 1u);
;             const unsigned tg = og / nx;
;             if (og + 1u == (tg + 1u) * nx) xb_add(&bar[XB_TOPGEN], 1u);
;             else XB_SPIN(xb_ld(&bar[XB_TOPGEN]) == tg, bar);
;             __builtin_amdgcn_fence(__ATOMIC_ACQUIRE, "agent");
;             xb_add(&bar[XB_XGEN(b.x)], 1u);
;             asm volatile("s_waitcnt vmcnt(0)" ::: "memory");
;         } else {
;             XB_SPIN(xb_ld(&bar[XB_XGEN(b.x)]) == gen, bar);
;             __builtin_amdgcn_fence(__ATOMIC_ACQUIRE, "agent");
;             asm volatile("s_waitcnt vmcnt(0)" ::: "memory");
;         }
.LBB0_1601:
	s_or_b64 exec, exec, s[10:11]
	v_cvt_f32_u32_e32 v4, v2
	s_waitcnt vmcnt(0)
	v_readfirstlane_b32 s0, v3
	v_sub_u32_e32 v3, 0, v2
	v_rcp_iflag_f32_e32 v4, v4
	v_add_u32_e32 v5, s0, v1
	v_mul_f32_e32 v4, 0x4f7ffffe, v4
	v_cvt_u32_f32_e32 v4, v4
	v_mul_lo_u32 v1, v3, v4
	v_mul_hi_u32 v1, v4, v1
	v_add_u32_e32 v1, v4, v1
	v_mul_hi_u32 v1, v5, v1
	v_mul_lo_u32 v3, v1, v2
	v_sub_u32_e32 v3, v5, v3
	v_add_u32_e32 v4, 1, v1
	v_cmp_ge_u32_e32 vcc, v3, v2
	s_nop 1
	v_cndmask_b32_e32 v1, v1, v4, vcc
	v_sub_u32_e32 v4, v3, v2
	v_cndmask_b32_e32 v3, v3, v4, vcc
	v_add_u32_e32 v4, 1, v1
	v_cmp_ge_u32_e32 vcc, v3, v2
	v_add_u32_e32 v3, 1, v5
	s_nop 0
	v_cndmask_b32_e32 v1, v1, v4, vcc
	v_mul_lo_u32 v4, v2, v1
	v_add_u32_e32 v2, v4, v2
	v_cmp_ne_u32_e32 vcc, v3, v2
	s_and_saveexec_b64 s[0:1], vcc
	s_xor_b64 s[8:9], exec, s[0:1]
	s_cbranch_execz .LBB0_1615
	s_waitcnt lgkmcnt(0)
	s_add_u32 s14, s70, 0xff20500
	s_addc_u32 s15, s71, 0
	v_mov_b32_e32 v0, 0
	global_load_dword v0, v0, s[14:15] sc1
	s_waitcnt vmcnt(0)
	v_cmp_eq_u32_e32 vcc, 1, v0
	s_and_saveexec_b64 s[10:11], vcc
	s_cbranch_execz .LBB0_1614
	s_add_u32 s12, s70, 0xff1d200
	s_addc_u32 s13, s71, 0
	s_mov_b32 s0, 1
	s_mov_b64 s[16:17], 0
	v_mov_b32_e32 v0, 0
	s_branch .LBB0_1605

; DI unsigned xb_ld(unsigned* p)              { return __hip_atomic_load(p, __ATOMIC_RELAXED, __HIP_MEMORY_SCOPE_AGENT); }
; #define XB_SPIN(cond, bar) do { unsigned _sp = 0; while (cond) { __builtin_amdgcn_s_sleep(1); \
;     if ((++_sp & 255u) == 0u) { if (xb_ld(&(bar)[XB_TMO])) break; if (_sp > XB_SPIN_CAP) { atomicAdd(&(bar)[XB_TMO], 1u); break; } } } } while (0)
; DI void xcd_barrier(const XcdBarrier& b) {
;     ...
;             XB_SPIN(xb_ld(&bar[XB_XGEN(b.x)]) == gen, bar);
.LBB0_1607:
	global_load_dword v2, v0, s[14:15] sc1
	s_add_i32 s0, s0, 1
	s_mov_b64 s[22:23], -1
	s_waitcnt vmcnt(0)
	v_cmp_ne_u32_e32 vcc, 1, v2
	s_orn2_b64 s[20:21], vcc, exec
	s_branch .LBB0_1604

; DI unsigned xb_ld(unsigned* p)              { return __hip_atomic_load(p, __ATOMIC_RELAXED, __HIP_MEMORY_SCOPE_AGENT); }
; DI unsigned xb_add(unsigned* p, unsigned v) { return __hip_atomic_fetch_add(p, v, __ATOMIC_RELAXED, __HIP_MEMORY_SCOPE_AGENT); }
; #define XB_SPIN(cond, bar) do { unsigned _sp = 0; while (cond) { __builtin_amdgcn_s_sleep(1); \
;     if ((++_sp & 255u) == 0u) { if (xb_ld(&(bar)[XB_TMO])) break; if (_sp > XB_SPIN_CAP) { atomicAdd(&(bar)[XB_TMO], 1u); break; } } } } while (0)
; DI void xcd_barrier(const XcdBarrier& b) {
;     ...
;         const unsigned old = xb_add(&bar[XB_XSUB(b.x)], 1u);
;         const unsigned gen = old / nloc;
;         if (old + 1u == (gen + 1u) * nloc) {
;             __builtin_amdgcn_fence(__ATOMIC_RELEASE, "agent");
;             asm volatile("s_waitcnt vmcnt(0)" ::: "memory");
;             const unsigned og = xb_add(&bar[XB_TOP], 1u);
;             const unsigned tg = og / nx;
;             if (og + 1u == (tg + 1u) * nx) xb_add(&bar[XB_TOPGEN], 1u);
;             else XB_SPIN(xb_ld(&bar[XB_TOPGEN]) == tg, bar);
;             __builtin_amdgcn_fence(__ATOMIC_ACQUIRE, "agent");
;             xb_add(&bar[XB_XGEN(b.x)], 1u);
;             asm volatile("s_waitcnt vmcnt(0)" ::: "memory");
;         } else {
;             XB_SPIN(xb_ld(&bar[XB_XGEN(b.x)]) == gen, bar);
;             __builtin_amdgcn_fence(__ATOMIC_ACQUIRE, "agent");
;             asm volatile("s_waitcnt vmcnt(0)" ::: "memory");
;         }
.LBB0_1762:
	s_or_b64 exec, exec, s[10:11]
	v_cvt_f32_u32_e32 v4, v2
	s_waitcnt vmcnt(0)
	v_readfirstlane_b32 s0, v3
	v_sub_u32_e32 v3, 0, v2
	v_rcp_iflag_f32_e32 v4, v4
	v_add_u32_e32 v5, s0, v1
	v_mul_f32_e32 v4, 0x4f7ffffe, v4
	v_cvt_u32_f32_e32 v4, v4
	v_mul_lo_u32 v1, v3, v4
	v_mul_hi_u32 v1, v4, v1
	v_add_u32_e32 v1, v4, v1
	v_mul_hi_u32 v1, v5, v1
	v_mul_lo_u32 v3, v1, v2
	v_sub_u32_e32 v3, v5, v3
	v_add_u32_e32 v4, 1, v1
	v_cmp_ge_u32_e32 vcc, v3, v2
	s_nop 1
	v_cndmask_b32_e32 v1, v1, v4, vcc
	v_sub_u32_e32 v4, v3, v2
	v_cndmask_b32_e32 v3, v3, v4, vcc
	v_add_u32_e32 v4, 1, v1
	v_cmp_ge_u32_e32 vcc, v3, v2
	v_add_u32_e32 v3, 1, v5
	s_nop 0
	v_cndmask_b32_e32 v1, v1, v4, vcc
	v_mul_lo_u32 v4, v2, v1
	v_add_u32_e32 v2, v4, v2
	v_cmp_ne_u32_e32 vcc, v3, v2
	s_and_saveexec_b64 s[0:1], vcc
	s_xor_b64 s[8:9], exec, s[0:1]
	s_cbranch_execz .LBB0_1776
	s_waitcnt lgkmcnt(0)
	s_add_u32 s14, s70, 0xff20500
	s_addc_u32 s15, s71, 0
	v_mov_b32_e32 v0, 0
	global_load_dword v0, v0, s[14:15] sc1
	s_waitcnt vmcnt(0)
	v_cmp_eq_u32_e32 vcc, 2, v0
	s_and_saveexec_b64 s[10:11], vcc
	s_cbranch_execz .LBB0_1775
	s_add_u32 s12, s70, 0xff1d200
	s_addc_u32 s13, s71, 0
	s_mov_b32 s0, 1
	s_mov_b64 s[16:17], 0
	v_mov_b32_e32 v0, 0
	s_branch .LBB0_1766

; DI unsigned xb_ld(unsigned* p)              { return __hip_atomic_load(p, __ATOMIC_RELAXED, __HIP_MEMORY_SCOPE_AGENT); }
; #define XB_SPIN(cond, bar) do { unsigned _sp = 0; while (cond) { __builtin_amdgcn_s_sleep(1); \
;     if ((++_sp & 255u) == 0u) { if (xb_ld(&(bar)[XB_TMO])) break; if (_sp > XB_SPIN_CAP) { atomicAdd(&(bar)[XB_TMO], 1u); break; } } } } while (0)
; DI void xcd_barrier(const XcdBarrier& b) {
;     ...
;             XB_SPIN(xb_ld(&bar[XB_XGEN(b.x)]) == gen, bar);
.LBB0_1768:
	global_load_dword v2, v0, s[14:15] sc1
	s_add_i32 s0, s0, 1
	s_mov_b64 s[22:23], -1
	s_waitcnt vmcnt(0)
	v_cmp_ne_u32_e32 vcc, 2, v2
	s_orn2_b64 s[20:21], vcc, exec
	s_branch .LBB0_1765

; DI unsigned xb_ld(unsigned* p)              { return __hip_atomic_load(p, __ATOMIC_RELAXED, __HIP_MEMORY_SCOPE_AGENT); }
; DI unsigned xb_add(unsigned* p, unsigned v) { return __hip_atomic_fetch_add(p, v, __ATOMIC_RELAXED, __HIP_MEMORY_SCOPE_AGENT); }
; #define XB_SPIN(cond, bar) do { unsigned _sp = 0; while (cond) { __builtin_amdgcn_s_sleep(1); \
;     if ((++_sp & 255u) == 0u) { if (xb_ld(&(bar)[XB_TMO])) break; if (_sp > XB_SPIN_CAP) { atomicAdd(&(bar)[XB_TMO], 1u); break; } } } } while (0)
; DI void xcd_barrier(const XcdBarrier& b) {
;     ...
;         const unsigned old = xb_add(&bar[XB_XSUB(b.x)], 1u);
;         const unsigned gen = old / nloc;
;         if (old + 1u == (gen + 1u) * nloc) {
;             __builtin_amdgcn_fence(__ATOMIC_RELEASE, "agent");
;             asm volatile("s_waitcnt vmcnt(0)" ::: "memory");
;             const unsigned og = xb_add(&bar[XB_TOP], 1u);
;             const unsigned tg = og / nx;
;             if (og + 1u == (tg + 1u) * nx) xb_add(&bar[XB_TOPGEN], 1u);
;             else XB_SPIN(xb_ld(&bar[XB_TOPGEN]) == tg, bar);
;             __builtin_amdgcn_fence(__ATOMIC_ACQUIRE, "agent");
;             xb_add(&bar[XB_XGEN(b.x)], 1u);
;             asm volatile("s_waitcnt vmcnt(0)" ::: "memory");
;         } else {
;             XB_SPIN(xb_ld(&bar[XB_XGEN(b.x)]) == gen, bar);
;             __builtin_amdgcn_fence(__ATOMIC_ACQUIRE, "agent");
;             asm volatile("s_waitcnt vmcnt(0)" ::: "memory");
;         }
.LBB0_1873:
	s_or_b64 exec, exec, s[10:11]
	v_cvt_f32_u32_e32 v4, v2
	s_waitcnt vmcnt(0)
	v_readfirstlane_b32 s0, v3
	v_sub_u32_e32 v3, 0, v2
	v_rcp_iflag_f32_e32 v4, v4
	v_add_u32_e32 v5, s0, v1
	v_mul_f32_e32 v4, 0x4f7ffffe, v4
	v_cvt_u32_f32_e32 v4, v4
	v_mul_lo_u32 v1, v3, v4
	v_mul_hi_u32 v1, v4, v1
	v_add_u32_e32 v1, v4, v1
	v_mul_hi_u32 v1, v5, v1
	v_mul_lo_u32 v3, v1, v2
	v_sub_u32_e32 v3, v5, v3
	v_add_u32_e32 v4, 1, v1
	v_cmp_ge_u32_e32 vcc, v3, v2
	s_nop 1
	v_cndmask_b32_e32 v1, v1, v4, vcc
	v_sub_u32_e32 v4, v3, v2
	v_cndmask_b32_e32 v3, v3, v4, vcc
	v_add_u32_e32 v4, 1, v1
	v_cmp_ge_u32_e32 vcc, v3, v2
	v_add_u32_e32 v3, 1, v5
	s_nop 0
	v_cndmask_b32_e32 v1, v1, v4, vcc
	v_mul_lo_u32 v4, v2, v1
	v_add_u32_e32 v2, v4, v2
	v_cmp_ne_u32_e32 vcc, v3, v2
	s_and_saveexec_b64 s[8:9], vcc
	s_xor_b64 s[8:9], exec, s[8:9]
	s_cbranch_execz .LBB0_1887
	s_waitcnt lgkmcnt(0)
	s_add_u32 s14, s70, 0xff20500
	s_addc_u32 s15, s71, 0
	v_mov_b32_e32 v0, 0
	global_load_dword v0, v0, s[14:15] sc1
	s_waitcnt vmcnt(0)
	v_cmp_eq_u32_e32 vcc, 3, v0
	s_and_saveexec_b64 s[10:11], vcc
	s_cbranch_execz .LBB0_1886
	s_add_u32 s12, s70, 0xff1d200
	s_addc_u32 s13, s71, 0
	s_mov_b32 s0, 1
	s_mov_b64 s[16:17], 0
	v_mov_b32_e32 v0, 0
	s_branch .LBB0_1877

; DI unsigned xb_ld(unsigned* p)              { return __hip_atomic_load(p, __ATOMIC_RELAXED, __HIP_MEMORY_SCOPE_AGENT); }
; #define XB_SPIN(cond, bar) do { unsigned _sp = 0; while (cond) { __builtin_amdgcn_s_sleep(1); \
;     if ((++_sp & 255u) == 0u) { if (xb_ld(&(bar)[XB_TMO])) break; if (_sp > XB_SPIN_CAP) { atomicAdd(&(bar)[XB_TMO], 1u); break; } } } } while (0)
; DI void xcd_barrier(const XcdBarrier& b) {
;     ...
;             XB_SPIN(xb_ld(&bar[XB_XGEN(b.x)]) == gen, bar);
.LBB0_1879:
	global_load_dword v2, v0, s[14:15] sc1
	s_add_i32 s0, s0, 1
	s_mov_b64 s[22:23], -1
	s_waitcnt vmcnt(0)
	v_cmp_ne_u32_e32 vcc, 3, v2
	s_orn2_b64 s[20:21], vcc, exec
	s_branch .LBB0_1876

; DI unsigned xb_ld(unsigned* p)              { return __hip_atomic_load(p, __ATOMIC_RELAXED, __HIP_MEMORY_SCOPE_AGENT); }
; DI unsigned xb_add(unsigned* p, unsigned v) { return __hip_atomic_fetch_add(p, v, __ATOMIC_RELAXED, __HIP_MEMORY_SCOPE_AGENT); }
; #define XB_SPIN(cond, bar) do { unsigned _sp = 0; while (cond) { __builtin_amdgcn_s_sleep(1); \
;     if ((++_sp & 255u) == 0u) { if (xb_ld(&(bar)[XB_TMO])) break; if (_sp > XB_SPIN_CAP) { atomicAdd(&(bar)[XB_TMO], 1u); break; } } } } while (0)
; DI void xcd_barrier(const XcdBarrier& b) {
;     ...
;         const unsigned old = xb_add(&bar[XB_XSUB(b.x)], 1u);
;         const unsigned gen = old / nloc;
;         if (old + 1u == (gen + 1u) * nloc) {
;             __builtin_amdgcn_fence(__ATOMIC_RELEASE, "agent");
;             asm volatile("s_waitcnt vmcnt(0)" ::: "memory");
;             const unsigned og = xb_add(&bar[XB_TOP], 1u);
;             const unsigned tg = og / nx;
;             if (og + 1u == (tg + 1u) * nx) xb_add(&bar[XB_TOPGEN], 1u);
;             else XB_SPIN(xb_ld(&bar[XB_TOPGEN]) == tg, bar);
;             __builtin_amdgcn_fence(__ATOMIC_ACQUIRE, "agent");
;             xb_add(&bar[XB_XGEN(b.x)], 1u);
;             asm volatile("s_waitcnt vmcnt(0)" ::: "memory");
;         } else {
;             XB_SPIN(xb_ld(&bar[XB_XGEN(b.x)]) == gen, bar);
;             __builtin_amdgcn_fence(__ATOMIC_ACQUIRE, "agent");
;             asm volatile("s_waitcnt vmcnt(0)" ::: "memory");
;         }
.LBB0_1957:
	s_or_b64 exec, exec, s[16:17]
	v_cvt_f32_u32_e32 v4, v2
	s_waitcnt vmcnt(0)
	v_readfirstlane_b32 s0, v3
	v_sub_u32_e32 v3, 0, v2
	v_rcp_iflag_f32_e32 v4, v4
	v_add_u32_e32 v5, s0, v1
	v_mul_f32_e32 v4, 0x4f7ffffe, v4
	v_cvt_u32_f32_e32 v4, v4
	v_mul_lo_u32 v1, v3, v4
	v_mul_hi_u32 v1, v4, v1
	v_add_u32_e32 v1, v4, v1
	v_mul_hi_u32 v1, v5, v1
	v_mul_lo_u32 v3, v1, v2
	v_sub_u32_e32 v3, v5, v3
	v_add_u32_e32 v4, 1, v1
	v_cmp_ge_u32_e32 vcc, v3, v2
	s_nop 1
	v_cndmask_b32_e32 v1, v1, v4, vcc
	v_sub_u32_e32 v4, v3, v2
	v_cndmask_b32_e32 v3, v3, v4, vcc
	v_add_u32_e32 v4, 1, v1
	v_cmp_ge_u32_e32 vcc, v3, v2
	v_add_u32_e32 v3, 1, v5
	s_nop 0
	v_cndmask_b32_e32 v1, v1, v4, vcc
	v_mul_lo_u32 v4, v2, v1
	v_add_u32_e32 v2, v4, v2
	v_cmp_ne_u32_e32 vcc, v3, v2
	s_and_saveexec_b64 s[0:1], vcc
	s_xor_b64 s[14:15], exec, s[0:1]
	s_cbranch_execz .LBB0_1971
	s_waitcnt lgkmcnt(0)
	s_add_u32 s20, s70, 0xff20500
	s_addc_u32 s21, s71, 0
	v_mov_b32_e32 v0, 0
	global_load_dword v0, v0, s[20:21] sc1
	s_waitcnt vmcnt(0)
	v_cmp_eq_u32_e32 vcc, 4, v0
	s_and_saveexec_b64 s[16:17], vcc
	s_cbranch_execz .LBB0_1970
	s_add_u32 s18, s70, 0xff1d200
	s_addc_u32 s19, s71, 0
	s_mov_b32 s0, 1
	s_mov_b64 s[22:23], 0
	v_mov_b32_e32 v0, 0
	s_branch .LBB0_1961

; DI unsigned xb_ld(unsigned* p)              { return __hip_atomic_load(p, __ATOMIC_RELAXED, __HIP_MEMORY_SCOPE_AGENT); }
; #define XB_SPIN(cond, bar) do { unsigned _sp = 0; while (cond) { __builtin_amdgcn_s_sleep(1); \
;     if ((++_sp & 255u) == 0u) { if (xb_ld(&(bar)[XB_TMO])) break; if (_sp > XB_SPIN_CAP) { atomicAdd(&(bar)[XB_TMO], 1u); break; } } } } while (0)
; DI void xcd_barrier(const XcdBarrier& b) {
;     ...
;             XB_SPIN(xb_ld(&bar[XB_XGEN(b.x)]) == gen, bar);
.LBB0_1963:
	global_load_dword v2, v0, s[20:21] sc1
	s_add_i32 s0, s0, 1
	s_mov_b64 s[28:29], -1
	s_waitcnt vmcnt(0)
	v_cmp_ne_u32_e32 vcc, 4, v2
	s_orn2_b64 s[26:27], vcc, exec
	s_branch .LBB0_1960
